# v77 + FFN1 SwiGLU epilogue: one reciprocal per pair of sigmoids (1/a0 = a1*rcp(a0*a1), exponent argument clamped at 62): 96 instead of 128 transcendentals per wave per tile
# baseline (speedup 1.0000x reference)
; __device__ __forceinline__ u32x4 pack8(const float (&o)[8]) { u32x4 r; r.x = pk2(o[0], o[1]); r.y = pk2(o[2], o[3]); r.z = pk2(o[4], o[5]); r.w = pk2(o[6], o[7]); return r; }
; __device__ __forceinline__ float silu_f(float v) { return v * __builtin_amdgcn_rcpf(1.f + __expf(-v)); }
;     __device__ __forceinline__ void operator()(const f32x4 (&acc)[2][2][4][2], const pg8::Unit& u, int wr, int wc, int fr, int fq, int) const {
;         const int row0 = u.pm * 256 + wr * 64 + fr, col0 = u.pn * 128 + wc * 32 + 8 * fq;
; #pragma unroll
;         for (int ai = 0; ai < 2; ++ai)
; #pragma unroll
;             for (int m = 0; m < 4; ++m) { bf16_t* rowp = O + (size_t)(row0 + ai * 128 + m * 16) * DFF + col0;
;                 float r[8];
; #pragma unroll
;                 for (int n = 0; n < 2; ++n)
; #pragma unroll
;                     for (int i = 0; i < 4; ++i) { const float gt = acc[ai][0][m][n][i], up = acc[ai][1][m][n][i]; r[n * 4 + i] = silu_f(gt) * up; }
;                 *(u32x4*)rowp = pack8(r); }
;     }
.LBB0_1053:
	v_lshl_or_b32 v166, s35, 7, v162
	v_lshl_add_u32 v164, s34, 8, v1
	v_mov_b32_e32 v252, 0xbfb8aa3b
	v_mov_b32_e32 v253, 0xbfb8aa3b
	v_ashrrev_i32_e32 v167, 31, v166
	v_mov_b64_e32 v[160:161], s[90:91]
	v_mov_b32_e32 v250, 1.0
	v_mov_b32_e32 v251, 1.0
	v_lshlrev_b64 v[166:167], 1, v[166:167]
	s_and_b64 vcc, exec, s[4:5]
	v_lshl_add_u64 v[160:161], v[160:161], 0, v[166:167]
	v_mad_i64_i32 v[200:201], s[12:13], v164, s80, v[160:161]
	v_pk_mul_f32 v[122:123], v[126:127], v[122:123]
	v_pk_mul_f32 v[124:125], v[128:129], v[124:125]
	v_pk_mul_f32 v[114:115], v[118:119], v[114:115]
	v_pk_mul_f32 v[116:117], v[120:121], v[116:117]
	v_pk_mul_f32 v[126:127], v[126:127], v[252:253]
	v_pk_mul_f32 v[128:129], v[128:129], v[252:253]
	v_pk_mul_f32 v[118:119], v[118:119], v[252:253]
	v_pk_mul_f32 v[120:121], v[120:121], v[252:253]
	v_min_f32_e32 v126, 0x42780000, v126
	v_min_f32_e32 v127, 0x42780000, v127
	v_min_f32_e32 v128, 0x42780000, v128
	v_min_f32_e32 v129, 0x42780000, v129
	v_min_f32_e32 v118, 0x42780000, v118
	v_min_f32_e32 v119, 0x42780000, v119
	v_min_f32_e32 v120, 0x42780000, v120
	v_min_f32_e32 v121, 0x42780000, v121
	v_exp_f32_e32 v126, v126
	v_exp_f32_e32 v127, v127
	v_exp_f32_e32 v128, v128
	v_exp_f32_e32 v129, v129
	v_exp_f32_e32 v118, v118
	v_exp_f32_e32 v119, v119
	v_exp_f32_e32 v120, v120
	v_exp_f32_e32 v121, v121
	v_pk_add_f32 v[126:127], v[126:127], v[250:251]
	v_pk_add_f32 v[128:129], v[128:129], v[250:251]
	v_pk_add_f32 v[118:119], v[118:119], v[250:251]
	v_pk_add_f32 v[120:121], v[120:121], v[250:251]
	v_mul_f32_e32 v168, v126, v127
	v_mul_f32_e32 v170, v128, v129
	v_mul_f32_e32 v172, v118, v119
	v_mul_f32_e32 v174, v120, v121
	v_rcp_f32_e32 v168, v168
	v_rcp_f32_e32 v170, v170
	v_rcp_f32_e32 v172, v172
	v_rcp_f32_e32 v174, v174
	v_pk_mul_f32 v[176:177], v[126:127], v[168:169] op_sel:[1,0] op_sel_hi:[0,0]
	v_pk_mul_f32 v[178:179], v[128:129], v[170:171] op_sel:[1,0] op_sel_hi:[0,0]
	v_pk_mul_f32 v[180:181], v[118:119], v[172:173] op_sel:[1,0] op_sel_hi:[0,0]
	v_pk_mul_f32 v[182:183], v[120:121], v[174:175] op_sel:[1,0] op_sel_hi:[0,0]
	v_pk_mul_f32 v[122:123], v[122:123], v[176:177]
	v_pk_mul_f32 v[124:125], v[124:125], v[178:179]
	v_pk_mul_f32 v[114:115], v[114:115], v[180:181]
	v_pk_mul_f32 v[116:117], v[116:117], v[182:183]
	v_cvt_pk_bf16_f32 v230, v122, v123
	v_cvt_pk_bf16_f32 v231, v124, v125
	v_cvt_pk_bf16_f32 v232, v114, v115
	v_cvt_pk_bf16_f32 v233, v116, v117
	global_store_dwordx4 v[200:201], v[230:233], off
	v_add_u32_e32 v221, 16, v164
	v_mad_i64_i32 v[202:203], s[12:13], v221, s80, v[160:161]
	v_pk_mul_f32 v[106:107], v[110:111], v[106:107]
	v_pk_mul_f32 v[108:109], v[112:113], v[108:109]
	v_pk_mul_f32 v[98:99], v[102:103], v[98:99]
	v_pk_mul_f32 v[100:101], v[104:105], v[100:101]
	v_pk_mul_f32 v[110:111], v[110:111], v[252:253]
	v_pk_mul_f32 v[112:113], v[112:113], v[252:253]
	v_pk_mul_f32 v[102:103], v[102:103], v[252:253]
	v_pk_mul_f32 v[104:105], v[104:105], v[252:253]
	v_min_f32_e32 v110, 0x42780000, v110
	v_min_f32_e32 v111, 0x42780000, v111
	v_min_f32_e32 v112, 0x42780000, v112
	v_min_f32_e32 v113, 0x42780000, v113
	v_min_f32_e32 v102, 0x42780000, v102
	v_min_f32_e32 v103, 0x42780000, v103
	v_min_f32_e32 v104, 0x42780000, v104
	v_min_f32_e32 v105, 0x42780000, v105
	v_exp_f32_e32 v110, v110
	v_exp_f32_e32 v111, v111
	v_exp_f32_e32 v112, v112
	v_exp_f32_e32 v113, v113
	v_exp_f32_e32 v102, v102
	v_exp_f32_e32 v103, v103
	v_exp_f32_e32 v104, v104
	v_exp_f32_e32 v105, v105
	v_pk_add_f32 v[110:111], v[110:111], v[250:251]
	v_pk_add_f32 v[112:113], v[112:113], v[250:251]
	v_pk_add_f32 v[102:103], v[102:103], v[250:251]
	v_pk_add_f32 v[104:105], v[104:105], v[250:251]
	v_mul_f32_e32 v168, v110, v111
	v_mul_f32_e32 v170, v112, v113
	v_mul_f32_e32 v172, v102, v103
	v_mul_f32_e32 v174, v104, v105
	v_rcp_f32_e32 v168, v168
	v_rcp_f32_e32 v170, v170
	v_rcp_f32_e32 v172, v172
	v_rcp_f32_e32 v174, v174
	v_pk_mul_f32 v[176:177], v[110:111], v[168:169] op_sel:[1,0] op_sel_hi:[0,0]
	v_pk_mul_f32 v[178:179], v[112:113], v[170:171] op_sel:[1,0] op_sel_hi:[0,0]
	v_pk_mul_f32 v[180:181], v[102:103], v[172:173] op_sel:[1,0] op_sel_hi:[0,0]
	v_pk_mul_f32 v[182:183], v[104:105], v[174:175] op_sel:[1,0] op_sel_hi:[0,0]
	v_pk_mul_f32 v[106:107], v[106:107], v[176:177]
	v_pk_mul_f32 v[108:109], v[108:109], v[178:179]
	v_pk_mul_f32 v[98:99], v[98:99], v[180:181]
	v_pk_mul_f32 v[100:101], v[100:101], v[182:183]
	v_cvt_pk_bf16_f32 v234, v106, v107
	v_cvt_pk_bf16_f32 v235, v108, v109
	v_cvt_pk_bf16_f32 v236, v98, v99
	v_cvt_pk_bf16_f32 v237, v100, v101
	global_store_dwordx4 v[202:203], v[234:237], off
	v_add_u32_e32 v222, 32, v164
	v_mad_i64_i32 v[204:205], s[12:13], v222, s80, v[160:161]
	v_pk_mul_f32 v[90:91], v[94:95], v[90:91]
	v_pk_mul_f32 v[92:93], v[96:97], v[92:93]
	v_pk_mul_f32 v[82:83], v[86:87], v[82:83]
	v_pk_mul_f32 v[84:85], v[88:89], v[84:85]
	v_pk_mul_f32 v[94:95], v[94:95], v[252:253]
	v_pk_mul_f32 v[96:97], v[96:97], v[252:253]
	v_pk_mul_f32 v[86:87], v[86:87], v[252:253]
	v_pk_mul_f32 v[88:89], v[88:89], v[252:253]
	v_min_f32_e32 v94, 0x42780000, v94
	v_min_f32_e32 v95, 0x42780000, v95
	v_min_f32_e32 v96, 0x42780000, v96
	v_min_f32_e32 v97, 0x42780000, v97
	v_min_f32_e32 v86, 0x42780000, v86
	v_min_f32_e32 v87, 0x42780000, v87
	v_min_f32_e32 v88, 0x42780000, v88
	v_min_f32_e32 v89, 0x42780000, v89
	v_exp_f32_e32 v94, v94
	v_exp_f32_e32 v95, v95
	v_exp_f32_e32 v96, v96
	v_exp_f32_e32 v97, v97
	v_exp_f32_e32 v86, v86
	v_exp_f32_e32 v87, v87
	v_exp_f32_e32 v88, v88
	v_exp_f32_e32 v89, v89
	v_pk_add_f32 v[94:95], v[94:95], v[250:251]
	v_pk_add_f32 v[96:97], v[96:97], v[250:251]
	v_pk_add_f32 v[86:87], v[86:87], v[250:251]
; __device__ __forceinline__ u32x4 pack8(const float (&o)[8]) { u32x4 r; r.x = pk2(o[0], o[1]); r.y = pk2(o[2], o[3]); r.z = pk2(o[4], o[5]); r.w = pk2(o[6], o[7]); return r; }
; __device__ __forceinline__ float silu_f(float v) { return v * __builtin_amdgcn_rcpf(1.f + __expf(-v)); }
;     __device__ __forceinline__ void operator()(const f32x4 (&acc)[2][2][4][2], const pg8::Unit& u, int wr, int wc, int fr, int fq, int) const {
;         const int row0 = u.pm * 256 + wr * 64 + fr, col0 = u.pn * 128 + wc * 32 + 8 * fq;
; #pragma unroll
;         for (int ai = 0; ai < 2; ++ai)
; #pragma unroll
;             for (int m = 0; m < 4; ++m) { bf16_t* rowp = O + (size_t)(row0 + ai * 128 + m * 16) * DFF + col0;
;                 float r[8];
; #pragma unroll
;                 for (int n = 0; n < 2; ++n)
; #pragma unroll
;                     for (int i = 0; i < 4; ++i) { const float gt = acc[ai][0][m][n][i], up = acc[ai][1][m][n][i]; r[n * 4 + i] = silu_f(gt) * up; }
;                 *(u32x4*)rowp = pack8(r); }
;     }
	v_pk_add_f32 v[88:89], v[88:89], v[250:251]
	v_mul_f32_e32 v168, v94, v95
	v_mul_f32_e32 v170, v96, v97
	v_mul_f32_e32 v172, v86, v87
	v_mul_f32_e32 v174, v88, v89
	v_rcp_f32_e32 v168, v168
	v_rcp_f32_e32 v170, v170
	v_rcp_f32_e32 v172, v172
	v_rcp_f32_e32 v174, v174
	v_pk_mul_f32 v[176:177], v[94:95], v[168:169] op_sel:[1,0] op_sel_hi:[0,0]
	v_pk_mul_f32 v[178:179], v[96:97], v[170:171] op_sel:[1,0] op_sel_hi:[0,0]
	v_pk_mul_f32 v[180:181], v[86:87], v[172:173] op_sel:[1,0] op_sel_hi:[0,0]
	v_pk_mul_f32 v[182:183], v[88:89], v[174:175] op_sel:[1,0] op_sel_hi:[0,0]
	v_pk_mul_f32 v[90:91], v[90:91], v[176:177]
	v_pk_mul_f32 v[92:93], v[92:93], v[178:179]
	v_pk_mul_f32 v[82:83], v[82:83], v[180:181]
	v_pk_mul_f32 v[84:85], v[84:85], v[182:183]
	v_cvt_pk_bf16_f32 v238, v90, v91
	v_cvt_pk_bf16_f32 v239, v92, v93
	v_cvt_pk_bf16_f32 v240, v82, v83
	v_cvt_pk_bf16_f32 v241, v84, v85
	global_store_dwordx4 v[204:205], v[238:241], off
	v_add_u32_e32 v223, 48, v164
	v_mad_i64_i32 v[206:207], s[12:13], v223, s80, v[160:161]
	v_pk_mul_f32 v[74:75], v[78:79], v[74:75]
	v_pk_mul_f32 v[76:77], v[80:81], v[76:77]
	v_pk_mul_f32 v[66:67], v[70:71], v[66:67]
	v_pk_mul_f32 v[68:69], v[72:73], v[68:69]
	v_pk_mul_f32 v[78:79], v[78:79], v[252:253]
	v_pk_mul_f32 v[80:81], v[80:81], v[252:253]
	v_pk_mul_f32 v[70:71], v[70:71], v[252:253]
	v_pk_mul_f32 v[72:73], v[72:73], v[252:253]
	v_min_f32_e32 v78, 0x42780000, v78
	v_min_f32_e32 v79, 0x42780000, v79
	v_min_f32_e32 v80, 0x42780000, v80
	v_min_f32_e32 v81, 0x42780000, v81
	v_min_f32_e32 v70, 0x42780000, v70
	v_min_f32_e32 v71, 0x42780000, v71
	v_min_f32_e32 v72, 0x42780000, v72
	v_min_f32_e32 v73, 0x42780000, v73
	v_exp_f32_e32 v78, v78
	v_exp_f32_e32 v79, v79
	v_exp_f32_e32 v80, v80
	v_exp_f32_e32 v81, v81
	v_exp_f32_e32 v70, v70
	v_exp_f32_e32 v71, v71
	v_exp_f32_e32 v72, v72
	v_exp_f32_e32 v73, v73
	v_pk_add_f32 v[78:79], v[78:79], v[250:251]
	v_pk_add_f32 v[80:81], v[80:81], v[250:251]
	v_pk_add_f32 v[70:71], v[70:71], v[250:251]
	v_pk_add_f32 v[72:73], v[72:73], v[250:251]
	v_mul_f32_e32 v168, v78, v79
	v_mul_f32_e32 v170, v80, v81
	v_mul_f32_e32 v172, v70, v71
	v_mul_f32_e32 v174, v72, v73
	v_rcp_f32_e32 v168, v168
	v_rcp_f32_e32 v170, v170
	v_rcp_f32_e32 v172, v172
	v_rcp_f32_e32 v174, v174
	v_pk_mul_f32 v[176:177], v[78:79], v[168:169] op_sel:[1,0] op_sel_hi:[0,0]
	v_pk_mul_f32 v[178:179], v[80:81], v[170:171] op_sel:[1,0] op_sel_hi:[0,0]
	v_pk_mul_f32 v[180:181], v[70:71], v[172:173] op_sel:[1,0] op_sel_hi:[0,0]
	v_pk_mul_f32 v[182:183], v[72:73], v[174:175] op_sel:[1,0] op_sel_hi:[0,0]
	v_pk_mul_f32 v[74:75], v[74:75], v[176:177]
	v_pk_mul_f32 v[76:77], v[76:77], v[178:179]
	v_pk_mul_f32 v[66:67], v[66:67], v[180:181]
	v_pk_mul_f32 v[68:69], v[68:69], v[182:183]
	v_cvt_pk_bf16_f32 v242, v74, v75
	v_cvt_pk_bf16_f32 v243, v76, v77
	v_cvt_pk_bf16_f32 v244, v66, v67
	v_cvt_pk_bf16_f32 v245, v68, v69
	global_store_dwordx4 v[206:207], v[242:245], off
	v_add_u32_e32 v224, 128, v164
	v_mad_i64_i32 v[208:209], s[12:13], v224, s80, v[160:161]
	v_pk_mul_f32 v[58:59], v[62:63], v[58:59]
	v_pk_mul_f32 v[60:61], v[64:65], v[60:61]
	v_pk_mul_f32 v[50:51], v[54:55], v[50:51]
	v_pk_mul_f32 v[52:53], v[56:57], v[52:53]
	v_pk_mul_f32 v[62:63], v[62:63], v[252:253]
	v_pk_mul_f32 v[64:65], v[64:65], v[252:253]
	v_pk_mul_f32 v[54:55], v[54:55], v[252:253]
	v_pk_mul_f32 v[56:57], v[56:57], v[252:253]
	v_min_f32_e32 v62, 0x42780000, v62
	v_min_f32_e32 v63, 0x42780000, v63
	v_min_f32_e32 v64, 0x42780000, v64
	v_min_f32_e32 v65, 0x42780000, v65
	v_min_f32_e32 v54, 0x42780000, v54
	v_min_f32_e32 v55, 0x42780000, v55
	v_min_f32_e32 v56, 0x42780000, v56
	v_min_f32_e32 v57, 0x42780000, v57
	v_exp_f32_e32 v62, v62
	v_exp_f32_e32 v63, v63
	v_exp_f32_e32 v64, v64
	v_exp_f32_e32 v65, v65
	v_exp_f32_e32 v54, v54
	v_exp_f32_e32 v55, v55
	v_exp_f32_e32 v56, v56
	v_exp_f32_e32 v57, v57
	v_pk_add_f32 v[62:63], v[62:63], v[250:251]
	v_pk_add_f32 v[64:65], v[64:65], v[250:251]
	v_pk_add_f32 v[54:55], v[54:55], v[250:251]
	v_pk_add_f32 v[56:57], v[56:57], v[250:251]
	v_mul_f32_e32 v168, v62, v63
	v_mul_f32_e32 v170, v64, v65
	v_mul_f32_e32 v172, v54, v55
	v_mul_f32_e32 v174, v56, v57
	v_rcp_f32_e32 v168, v168
	v_rcp_f32_e32 v170, v170
	v_rcp_f32_e32 v172, v172
	v_rcp_f32_e32 v174, v174
	v_pk_mul_f32 v[176:177], v[62:63], v[168:169] op_sel:[1,0] op_sel_hi:[0,0]
	v_pk_mul_f32 v[178:179], v[64:65], v[170:171] op_sel:[1,0] op_sel_hi:[0,0]
	v_pk_mul_f32 v[180:181], v[54:55], v[172:173] op_sel:[1,0] op_sel_hi:[0,0]
	v_pk_mul_f32 v[182:183], v[56:57], v[174:175] op_sel:[1,0] op_sel_hi:[0,0]
	v_pk_mul_f32 v[58:59], v[58:59], v[176:177]
	v_pk_mul_f32 v[60:61], v[60:61], v[178:179]
	v_pk_mul_f32 v[50:51], v[50:51], v[180:181]
	v_pk_mul_f32 v[52:53], v[52:53], v[182:183]
	v_cvt_pk_bf16_f32 v230, v58, v59
	v_cvt_pk_bf16_f32 v231, v60, v61
	v_cvt_pk_bf16_f32 v232, v50, v51
	v_cvt_pk_bf16_f32 v233, v52, v53
	global_store_dwordx4 v[208:209], v[230:233], off
	v_add_u32_e32 v225, 144, v164
	v_mad_i64_i32 v[210:211], s[12:13], v225, s80, v[160:161]
	v_pk_mul_f32 v[42:43], v[46:47], v[42:43]
	v_pk_mul_f32 v[44:45], v[48:49], v[44:45]
	v_pk_mul_f32 v[34:35], v[38:39], v[34:35]
	v_pk_mul_f32 v[36:37], v[40:41], v[36:37]
	v_pk_mul_f32 v[46:47], v[46:47], v[252:253]
	v_pk_mul_f32 v[48:49], v[48:49], v[252:253]
	v_pk_mul_f32 v[38:39], v[38:39], v[252:253]
	v_pk_mul_f32 v[40:41], v[40:41], v[252:253]
	v_min_f32_e32 v46, 0x42780000, v46
	v_min_f32_e32 v47, 0x42780000, v47
	v_min_f32_e32 v48, 0x42780000, v48
; __device__ __forceinline__ u32x4 pack8(const float (&o)[8]) { u32x4 r; r.x = pk2(o[0], o[1]); r.y = pk2(o[2], o[3]); r.z = pk2(o[4], o[5]); r.w = pk2(o[6], o[7]); return r; }
; __device__ __forceinline__ float silu_f(float v) { return v * __builtin_amdgcn_rcpf(1.f + __expf(-v)); }
;     __device__ __forceinline__ void operator()(const f32x4 (&acc)[2][2][4][2], const pg8::Unit& u, int wr, int wc, int fr, int fq, int) const {
;         const int row0 = u.pm * 256 + wr * 64 + fr, col0 = u.pn * 128 + wc * 32 + 8 * fq;
; #pragma unroll
;         for (int ai = 0; ai < 2; ++ai)
; #pragma unroll
;             for (int m = 0; m < 4; ++m) { bf16_t* rowp = O + (size_t)(row0 + ai * 128 + m * 16) * DFF + col0;
;                 float r[8];
; #pragma unroll
;                 for (int n = 0; n < 2; ++n)
; #pragma unroll
;                     for (int i = 0; i < 4; ++i) { const float gt = acc[ai][0][m][n][i], up = acc[ai][1][m][n][i]; r[n * 4 + i] = silu_f(gt) * up; }
;                 *(u32x4*)rowp = pack8(r); }
	v_min_f32_e32 v49, 0x42780000, v49
	v_min_f32_e32 v38, 0x42780000, v38
	v_min_f32_e32 v39, 0x42780000, v39
	v_min_f32_e32 v40, 0x42780000, v40
	v_min_f32_e32 v41, 0x42780000, v41
	v_exp_f32_e32 v46, v46
	v_exp_f32_e32 v47, v47
	v_exp_f32_e32 v48, v48
	v_exp_f32_e32 v49, v49
	v_exp_f32_e32 v38, v38
	v_exp_f32_e32 v39, v39
	v_exp_f32_e32 v40, v40
	v_exp_f32_e32 v41, v41
	v_pk_add_f32 v[46:47], v[46:47], v[250:251]
	v_pk_add_f32 v[48:49], v[48:49], v[250:251]
	v_pk_add_f32 v[38:39], v[38:39], v[250:251]
	v_pk_add_f32 v[40:41], v[40:41], v[250:251]
	v_mul_f32_e32 v168, v46, v47
	v_mul_f32_e32 v170, v48, v49
	v_mul_f32_e32 v172, v38, v39
	v_mul_f32_e32 v174, v40, v41
	v_rcp_f32_e32 v168, v168
	v_rcp_f32_e32 v170, v170
	v_rcp_f32_e32 v172, v172
	v_rcp_f32_e32 v174, v174
	v_pk_mul_f32 v[176:177], v[46:47], v[168:169] op_sel:[1,0] op_sel_hi:[0,0]
	v_pk_mul_f32 v[178:179], v[48:49], v[170:171] op_sel:[1,0] op_sel_hi:[0,0]
	v_pk_mul_f32 v[180:181], v[38:39], v[172:173] op_sel:[1,0] op_sel_hi:[0,0]
	v_pk_mul_f32 v[182:183], v[40:41], v[174:175] op_sel:[1,0] op_sel_hi:[0,0]
	v_pk_mul_f32 v[42:43], v[42:43], v[176:177]
	v_pk_mul_f32 v[44:45], v[44:45], v[178:179]
	v_pk_mul_f32 v[34:35], v[34:35], v[180:181]
	v_pk_mul_f32 v[36:37], v[36:37], v[182:183]
	v_cvt_pk_bf16_f32 v234, v42, v43
	v_cvt_pk_bf16_f32 v235, v44, v45
	v_cvt_pk_bf16_f32 v236, v34, v35
	v_cvt_pk_bf16_f32 v237, v36, v37
	global_store_dwordx4 v[210:211], v[234:237], off
	v_add_u32_e32 v226, 160, v164
	v_mad_i64_i32 v[212:213], s[12:13], v226, s80, v[160:161]
	v_pk_mul_f32 v[26:27], v[30:31], v[26:27]
	v_pk_mul_f32 v[28:29], v[32:33], v[28:29]
	v_pk_mul_f32 v[18:19], v[22:23], v[18:19]
	v_pk_mul_f32 v[20:21], v[24:25], v[20:21]
	v_pk_mul_f32 v[30:31], v[30:31], v[252:253]
	v_pk_mul_f32 v[32:33], v[32:33], v[252:253]
	v_pk_mul_f32 v[22:23], v[22:23], v[252:253]
	v_pk_mul_f32 v[24:25], v[24:25], v[252:253]
	v_min_f32_e32 v30, 0x42780000, v30
	v_min_f32_e32 v31, 0x42780000, v31
	v_min_f32_e32 v32, 0x42780000, v32
	v_min_f32_e32 v33, 0x42780000, v33
	v_min_f32_e32 v22, 0x42780000, v22
	v_min_f32_e32 v23, 0x42780000, v23
	v_min_f32_e32 v24, 0x42780000, v24
	v_min_f32_e32 v25, 0x42780000, v25
	v_exp_f32_e32 v30, v30
	v_exp_f32_e32 v31, v31
	v_exp_f32_e32 v32, v32
	v_exp_f32_e32 v33, v33
	v_exp_f32_e32 v22, v22
	v_exp_f32_e32 v23, v23
	v_exp_f32_e32 v24, v24
	v_exp_f32_e32 v25, v25
	v_pk_add_f32 v[30:31], v[30:31], v[250:251]
	v_pk_add_f32 v[32:33], v[32:33], v[250:251]
	v_pk_add_f32 v[22:23], v[22:23], v[250:251]
	v_pk_add_f32 v[24:25], v[24:25], v[250:251]
	v_mul_f32_e32 v168, v30, v31
	v_mul_f32_e32 v170, v32, v33
	v_mul_f32_e32 v172, v22, v23
	v_mul_f32_e32 v174, v24, v25
	v_rcp_f32_e32 v168, v168
	v_rcp_f32_e32 v170, v170
	v_rcp_f32_e32 v172, v172
	v_rcp_f32_e32 v174, v174
	v_pk_mul_f32 v[176:177], v[30:31], v[168:169] op_sel:[1,0] op_sel_hi:[0,0]
	v_pk_mul_f32 v[178:179], v[32:33], v[170:171] op_sel:[1,0] op_sel_hi:[0,0]
	v_pk_mul_f32 v[180:181], v[22:23], v[172:173] op_sel:[1,0] op_sel_hi:[0,0]
	v_pk_mul_f32 v[182:183], v[24:25], v[174:175] op_sel:[1,0] op_sel_hi:[0,0]
	v_pk_mul_f32 v[26:27], v[26:27], v[176:177]
	v_pk_mul_f32 v[28:29], v[28:29], v[178:179]
	v_pk_mul_f32 v[18:19], v[18:19], v[180:181]
	v_pk_mul_f32 v[20:21], v[20:21], v[182:183]
	v_cvt_pk_bf16_f32 v238, v26, v27
	v_cvt_pk_bf16_f32 v239, v28, v29
	v_cvt_pk_bf16_f32 v240, v18, v19
	v_cvt_pk_bf16_f32 v241, v20, v21
	global_store_dwordx4 v[212:213], v[238:241], off
	v_add_u32_e32 v227, 176, v164
	v_mad_i64_i32 v[214:215], s[12:13], v227, s80, v[160:161]
	v_pk_mul_f32 v[10:11], v[14:15], v[10:11]
	v_pk_mul_f32 v[12:13], v[16:17], v[12:13]
	v_pk_mul_f32 v[2:3], v[6:7], v[2:3]
	v_pk_mul_f32 v[4:5], v[8:9], v[4:5]
	v_pk_mul_f32 v[14:15], v[14:15], v[252:253]
	v_pk_mul_f32 v[16:17], v[16:17], v[252:253]
	v_pk_mul_f32 v[6:7], v[6:7], v[252:253]
	v_pk_mul_f32 v[8:9], v[8:9], v[252:253]
	v_min_f32_e32 v14, 0x42780000, v14
	v_min_f32_e32 v15, 0x42780000, v15
	v_min_f32_e32 v16, 0x42780000, v16
	v_min_f32_e32 v17, 0x42780000, v17
	v_min_f32_e32 v6, 0x42780000, v6
	v_min_f32_e32 v7, 0x42780000, v7
	v_min_f32_e32 v8, 0x42780000, v8
	v_min_f32_e32 v9, 0x42780000, v9
	v_exp_f32_e32 v14, v14
	v_exp_f32_e32 v15, v15
	v_exp_f32_e32 v16, v16
	v_exp_f32_e32 v17, v17
	v_exp_f32_e32 v6, v6
	v_exp_f32_e32 v7, v7
	v_exp_f32_e32 v8, v8
	v_exp_f32_e32 v9, v9
	v_pk_add_f32 v[14:15], v[14:15], v[250:251]
	v_pk_add_f32 v[16:17], v[16:17], v[250:251]
	v_pk_add_f32 v[6:7], v[6:7], v[250:251]
	v_pk_add_f32 v[8:9], v[8:9], v[250:251]
	v_mul_f32_e32 v168, v14, v15
	v_mul_f32_e32 v170, v16, v17
	v_mul_f32_e32 v172, v6, v7
	v_mul_f32_e32 v174, v8, v9
	v_rcp_f32_e32 v168, v168
	v_rcp_f32_e32 v170, v170
	v_rcp_f32_e32 v172, v172
	v_rcp_f32_e32 v174, v174
	v_pk_mul_f32 v[176:177], v[14:15], v[168:169] op_sel:[1,0] op_sel_hi:[0,0]
	v_pk_mul_f32 v[178:179], v[16:17], v[170:171] op_sel:[1,0] op_sel_hi:[0,0]
	v_pk_mul_f32 v[180:181], v[6:7], v[172:173] op_sel:[1,0] op_sel_hi:[0,0]
	v_pk_mul_f32 v[182:183], v[8:9], v[174:175] op_sel:[1,0] op_sel_hi:[0,0]
	v_pk_mul_f32 v[10:11], v[10:11], v[176:177]
	v_pk_mul_f32 v[12:13], v[12:13], v[178:179]
	v_pk_mul_f32 v[2:3], v[2:3], v[180:181]
	v_pk_mul_f32 v[4:5], v[4:5], v[182:183]
	v_cvt_pk_bf16_f32 v242, v10, v11
	v_cvt_pk_bf16_f32 v243, v12, v13
	v_cvt_pk_bf16_f32 v244, v2, v3
	v_cvt_pk_bf16_f32 v245, v4, v5
	global_store_dwordx4 v[214:215], v[242:245], off
	s_mov_b64 s[12:13], -1
	s_cbranch_vccnz .LBB0_1042
	s_branch .LBB0_1041
